# select: next unit's q/w loads and first two key chunks staged before select256 (cross-unit prefetch)
# speedup vs baseline: 1.0033x; 1.0007x over previous
.LBB0_885:
	s_and_b64 vcc, exec, s[4:5]
	s_cbranch_vccz .LBB0_1389
	s_cmpk_gt_i32 s95, 0x7ff
	s_cbranch_scc1 .LBB0_1389
	v_lshlrev_b32_e32 v0, 7, v242
	v_and_b32_e32 v0, 0x380, v0
	v_lshl_add_u64 v[2:3], s[58:59], 0, v[0:1]
	v_and_b32_e32 v0, 0x70, v242
	v_lshl_add_u64 v[2:3], v[2:3], 0, v[0:1]
	s_waitcnt lgkmcnt(0)
	s_mov_b64 s[8:9], 0x19390000
	v_and_b32_e32 v0, 16, v242
	v_lshl_add_u64 v[14:15], v[2:3], 0, s[8:9]
	v_lshl_add_u64 v[2:3], s[58:59], 0, v[0:1]
	s_mov_b64 s[8:9], 0x1bf90000
	s_ashr_i32 s55, s54, 31
	v_lshl_add_u64 v[16:17], v[2:3], 0, s[8:9]
	v_lshlrev_b32_e32 v2, 4, v242
	s_movk_i32 s8, 0x70
	s_lshl_b64 s[4:5], s[54:55], 14
	s_lshl_b32 s10, s1, 1
	v_and_b32_e32 v4, 15, v242
	v_lshrrev_b32_e32 v5, 4, v242
	v_lshlrev_b32_e32 v0, 4, v243
	v_bitop3_b32 v2, v243, s8, v2 bitop3:0x48
	s_movk_i32 s8, 0xff80
	v_lshrrev_b32_e32 v3, 1, v242
	v_and_or_b32 v0, v0, s8, v2
	s_add_u32 s16, s58, 0x1bb90000
	v_lshlrev_b32_e32 v2, 7, v4
	v_bitop3_b32 v4, v3, v5, 7 bitop3:0x6c
	s_addc_u32 s17, s59, 0
	v_lshl_or_b32 v124, v4, 4, v2
	v_add_u32_e32 v4, 4, v5
	s_add_u32 s4, s58, s4
	v_bitop3_b32 v3, v4, v3, 7 bitop3:0x78
	s_addc_u32 s5, s59, s5
	v_lshl_add_u32 v125, v3, 4, v2
	v_lshlrev_b32_e32 v2, 2, v242
	v_mov_b32_e32 v3, v1
	v_lshl_add_u64 v[2:3], s[4:5], 0, v[2:3]
	s_mov_b64 s[4:5], 0x1d090000
	v_lshl_add_u64 v[24:25], v[2:3], 0, s[4:5]
	s_mov_b64 s[4:5], 0x1d091000
	v_lshl_add_u64 v[26:27], v[2:3], 0, s[4:5]
	s_mov_b64 s[4:5], 0x1d091100
	v_lshl_add_u64 v[28:29], v[2:3], 0, s[4:5]
	s_mov_b64 s[4:5], 0x1d091200
	v_lshl_add_u64 v[30:31], v[2:3], 0, s[4:5]
	s_mov_b64 s[4:5], 0x1d091300
	v_lshl_add_u64 v[32:33], v[2:3], 0, s[4:5]
	s_mov_b64 s[4:5], 0x1d091400
	v_lshl_add_u64 v[34:35], v[2:3], 0, s[4:5]
	s_mov_b64 s[4:5], 0x1d091500
	v_lshl_add_u64 v[36:37], v[2:3], 0, s[4:5]
	s_mov_b64 s[4:5], 0x1d091600
	v_lshl_add_u64 v[38:39], v[2:3], 0, s[4:5]
	s_mov_b64 s[4:5], 0x1d091700
	v_lshl_add_u64 v[40:41], v[2:3], 0, s[4:5]
	s_mov_b64 s[4:5], 0x1d091800
	v_lshl_add_u64 v[42:43], v[2:3], 0, s[4:5]
	s_mov_b64 s[4:5], 0x1d091900
	v_lshl_add_u64 v[44:45], v[2:3], 0, s[4:5]
	s_mov_b64 s[4:5], 0x1d091a00
	v_lshl_add_u64 v[46:47], v[2:3], 0, s[4:5]
	s_mov_b64 s[4:5], 0x1d091b00
	v_lshl_add_u64 v[48:49], v[2:3], 0, s[4:5]
	s_mov_b64 s[4:5], 0x1d091c00
	v_lshl_add_u64 v[50:51], v[2:3], 0, s[4:5]
	s_mov_b64 s[4:5], 0x1d091d00
	v_lshl_add_u64 v[52:53], v[2:3], 0, s[4:5]
	s_mov_b64 s[4:5], 0x1d091e00
	v_lshl_add_u64 v[54:55], v[2:3], 0, s[4:5]
	s_mov_b64 s[4:5], 0x1d091f00
	v_lshl_add_u64 v[56:57], v[2:3], 0, s[4:5]
	s_mov_b64 s[4:5], 0x1d092000
	v_lshl_add_u64 v[58:59], v[2:3], 0, s[4:5]
	s_mov_b64 s[4:5], 0x1d092100
	v_lshl_add_u64 v[60:61], v[2:3], 0, s[4:5]
	s_mov_b64 s[4:5], 0x1d092200
	v_lshl_add_u64 v[62:63], v[2:3], 0, s[4:5]
	s_mov_b64 s[4:5], 0x1d092300
	v_lshl_add_u64 v[64:65], v[2:3], 0, s[4:5]
	s_mov_b64 s[4:5], 0x1d092400
	v_lshl_add_u64 v[66:67], v[2:3], 0, s[4:5]
	s_mov_b64 s[4:5], 0x1d092500
	v_lshl_add_u64 v[68:69], v[2:3], 0, s[4:5]
	s_mov_b64 s[4:5], 0x1d092600
	v_lshl_add_u64 v[70:71], v[2:3], 0, s[4:5]
	s_mov_b64 s[4:5], 0x1d092700
	v_lshl_add_u64 v[72:73], v[2:3], 0, s[4:5]
	s_mov_b64 s[4:5], 0x1d092800
	v_lshl_add_u64 v[74:75], v[2:3], 0, s[4:5]
	s_mov_b64 s[4:5], 0x1d092900
	v_lshl_add_u64 v[76:77], v[2:3], 0, s[4:5]
	s_mov_b64 s[4:5], 0x1d092a00
	v_lshl_add_u64 v[78:79], v[2:3], 0, s[4:5]
	s_mov_b64 s[4:5], 0x1d092b00
	v_lshl_add_u64 v[80:81], v[2:3], 0, s[4:5]
	s_mov_b64 s[4:5], 0x1d092c00
	v_lshl_add_u64 v[82:83], v[2:3], 0, s[4:5]
	s_mov_b64 s[4:5], 0x1d092d00
	v_lshl_add_u64 v[84:85], v[2:3], 0, s[4:5]
	s_mov_b64 s[4:5], 0x1d092e00
	v_lshl_add_u64 v[86:87], v[2:3], 0, s[4:5]
	s_mov_b64 s[4:5], 0x1d092f00
	v_lshl_add_u64 v[88:89], v[2:3], 0, s[4:5]
	s_mov_b64 s[4:5], 0x1d093000
	v_lshl_add_u64 v[90:91], v[2:3], 0, s[4:5]
	s_mov_b64 s[4:5], 0x1d093100
	v_lshl_add_u64 v[92:93], v[2:3], 0, s[4:5]
	s_mov_b64 s[4:5], 0x1d093200
	v_lshl_add_u64 v[94:95], v[2:3], 0, s[4:5]
	s_mov_b64 s[4:5], 0x1d093300
	v_lshl_add_u64 v[96:97], v[2:3], 0, s[4:5]
	s_mov_b64 s[4:5], 0x1d093400
	v_lshl_add_u64 v[98:99], v[2:3], 0, s[4:5]
	s_mov_b64 s[4:5], 0x1d093500
	v_lshl_add_u64 v[100:101], v[2:3], 0, s[4:5]
	s_mov_b64 s[4:5], 0x1d093600
	v_lshl_add_u64 v[102:103], v[2:3], 0, s[4:5]
	s_mov_b64 s[4:5], 0x1d093700
	v_lshl_add_u64 v[104:105], v[2:3], 0, s[4:5]
	s_mov_b64 s[4:5], 0x1d093800
	v_lshl_add_u64 v[106:107], v[2:3], 0, s[4:5]
	s_mov_b64 s[4:5], 0x1d093900
	v_lshl_add_u64 v[108:109], v[2:3], 0, s[4:5]
	s_mov_b64 s[4:5], 0x1d093a00
	v_lshl_add_u64 v[110:111], v[2:3], 0, s[4:5]
	s_mov_b64 s[4:5], 0x1d093b00
	v_lshl_add_u64 v[112:113], v[2:3], 0, s[4:5]
	s_mov_b64 s[4:5], 0x1d093c00
	v_lshl_add_u64 v[114:115], v[2:3], 0, s[4:5]
	s_mov_b64 s[4:5], 0x1d093d00
	v_lshl_add_u64 v[116:117], v[2:3], 0, s[4:5]
	s_mov_b64 s[4:5], 0x1d093e00
	v_lshl_add_u64 v[118:119], v[2:3], 0, s[4:5]
	s_mov_b64 s[4:5], 0x1d093f00
	s_lshl_b32 s1, s1, 10
	v_lshl_add_u64 v[120:121], v[2:3], 0, s[4:5]
	v_lshlrev_b32_e32 v2, 3, v242
	v_mov_b32_e32 v3, v1
	s_add_i32 s1, s1, 0
	v_lshl_add_u64 v[2:3], s[58:59], 0, v[2:3]
	s_mov_b64 s[4:5], 0x1c090000
	v_add_u32_e32 v18, 0x2000, v0
	v_add_u32_e32 v20, 0x4000, v0
	v_add_u32_e32 v22, 0x6000, v0
	v_mov_b32_e32 v19, v1
	v_mov_b32_e32 v21, v1
	v_mov_b32_e32 v23, v1
	v_cmp_gt_u32_e64 s[40:41], 16, v242
	v_cmp_eq_u32_e64 s[42:43], 1, v5
	v_cmp_eq_u32_e64 s[44:45], 2, v5
	s_add_i32 s29, s1, 0x10000
	s_add_i32 s52, s1, 0x12000
	s_add_i32 s53, s1, 0x14000
	s_add_i32 s54, s1, 0x16000
	v_add_u32_e32 v126, 0, v124
	v_add_u32_e32 v127, 0, v125
	v_add_u32_e32 v128, 64, v242
	v_or_b32_e32 v129, 0x80, v242
	v_add_u32_e32 v130, 0xc0, v242
	s_add_i32 s55, s1, 0x18000
	s_add_i32 s62, s1, 0x1a000
	s_add_i32 s63, s1, 0x1c000
	s_add_i32 s64, s1, 0x1e000
	v_or_b32_e32 v203, 0x100, v242
	v_add_u32_e32 v176, 0xc40, v242
	v_or_b32_e32 v177, 0xc80, v242
	v_add_u32_e32 v178, 0xcc0, v242
	v_or_b32_e32 v179, 0xd00, v242
	v_add_u32_e32 v180, 0xd40, v242
	v_or_b32_e32 v181, 0xd80, v242
	v_add_u32_e32 v182, 0xdc0, v242
	v_or_b32_e32 v183, 0xe00, v242
	v_add_u32_e32 v184, 0xe40, v242
	v_or_b32_e32 v185, 0xe80, v242
	v_add_u32_e32 v186, 0xec0, v242
	v_or_b32_e32 v187, 0xf00, v242
	v_add_u32_e32 v188, 0xf40, v242
	v_or_b32_e32 v189, 0xf80, v242
	v_add_u32_e32 v190, 0xfc0, v242
	v_lshl_add_u64 v[122:123], v[2:3], 0, s[4:5]
	s_mov_b32 s65, s95
	s_lshl_b32 s53, s65, 4
	s_and_b32 s53, s53, 0xff0
	s_ashr_i32 s54, s65, 8
	s_and_b32 s55, s65, 0x100
	s_xor_b32 s62, s53, 0xff0
	s_cmp_eq_u32 s55, 0
	s_cselect_b32 s53, s53, s62
	s_add_i32 s55, s53, s10
	s_lshl_b32 s62, s54, 12
	s_add_i32 s55, s55, s62
	v_bfe_u32 v170, v242, 3, 1
	v_or_b32_e32 v170, s55, v170
	v_ashrrev_i32_e32 v171, 31, v170
	v_lshlrev_b64 v[170:171], 10, v[170:171]
	v_lshl_add_u64 v[170:171], v[14:15], 0, v[170:171]
	global_load_dwordx4 v[98:101], v[170:171], off
	global_load_dwordx4 v[94:97], v[170:171], off offset:64
	v_lshrrev_b32_e32 v170, 5, v242
	v_add_u32_e32 v170, s55, v170
	v_ashrrev_i32_e32 v171, 31, v170
	v_lshlrev_b64 v[170:171], 5, v[170:171]
	v_lshl_add_u64 v[170:171], v[16:17], 0, v[170:171]
	global_load_dwordx4 v[90:93], v[170:171], off
	s_lshl_b32 s54, s54, 19
	s_add_u32 s62, s16, s54
	s_addc_u32 s63, s17, 0
	v_lshl_add_u64 v[170:171], s[62:63], 0, v[0:1]
	s_add_i32 m0, s1, 0x0
	s_nop 0
	global_load_lds_dwordx4 v[170:171], off
	v_lshl_add_u64 v[170:171], s[62:63], 0, v[18:19]
	s_add_i32 m0, s1, 0x2000
	s_nop 0
	global_load_lds_dwordx4 v[170:171], off
	v_lshl_add_u64 v[170:171], s[62:63], 0, v[20:21]
	s_add_i32 m0, s1, 0x4000
	s_nop 0
	global_load_lds_dwordx4 v[170:171], off
	v_lshl_add_u64 v[170:171], s[62:63], 0, v[22:23]
	s_add_i32 m0, s1, 0x6000
	s_nop 0
	global_load_lds_dwordx4 v[170:171], off
	s_cmpk_lt_u32 s53, 0xf1
	s_cbranch_scc1 .Lstg_donef
	s_add_u32 s62, s62, 0x8000
	s_addc_u32 s63, s63, 0
	v_lshl_add_u64 v[170:171], s[62:63], 0, v[0:1]
	s_add_i32 m0, s1, 0x8000
	s_nop 0
	global_load_lds_dwordx4 v[170:171], off
	v_lshl_add_u64 v[170:171], s[62:63], 0, v[18:19]
	s_add_i32 m0, s1, 0xa000
	s_nop 0
	global_load_lds_dwordx4 v[170:171], off
	v_lshl_add_u64 v[170:171], s[62:63], 0, v[20:21]
	s_add_i32 m0, s1, 0xc000
	s_nop 0
	global_load_lds_dwordx4 v[170:171], off
	v_lshl_add_u64 v[170:171], s[62:63], 0, v[22:23]
	s_add_i32 m0, s1, 0xe000
	s_nop 0
	global_load_lds_dwordx4 v[170:171], off
.Lstg_donef:
	s_waitcnt vmcnt(0)
	s_branch .LBB0_889

.LBB0_889:
	s_lshl_b32 s8, s65, 4
	s_and_b32 s8, s8, 0xff0
	s_ashr_i32 s4, s65, 8
	s_and_b32 s5, s65, 0x100
	s_xor_b32 s9, s8, 0xff0
	s_cmp_eq_u32 s5, 0
	s_cselect_b32 s66, s8, s9
	s_lshr_b32 s101, s66, 9
	s_ashr_i32 s5, s4, 31
	s_lshl_b64 s[8:9], s[4:5], 19
	s_add_i32 s57, s66, s10
	s_lshl_b32 s4, s4, 12
	s_add_i32 s56, s57, s4
	s_add_u32 s48, s16, s8
	s_addc_u32 s49, s17, s9
	v_mov_b32_e32 v2, v90
	v_mov_b32_e32 v3, v91
	v_mov_b32_e32 v4, v92
	v_mov_b32_e32 v5, v93
	v_mov_b32_e32 v6, v94
	v_mov_b32_e32 v7, v95
	v_mov_b32_e32 v8, v96
	v_mov_b32_e32 v9, v97
	v_mov_b32_e32 v10, v98
	v_mov_b32_e32 v11, v99
	v_mov_b32_e32 v12, v100
	v_mov_b32_e32 v13, v101

.Lsc_tail:
	global_load_dword v26, v168, s[8:9]
	global_load_dword v27, v168, s[8:9] offset:256
	global_load_dword v28, v168, s[8:9] offset:512
	global_load_dword v29, v168, s[8:9] offset:768
	global_load_dword v30, v168, s[8:9] offset:1024
	global_load_dword v31, v168, s[8:9] offset:1280
	global_load_dword v32, v168, s[8:9] offset:1536
	global_load_dword v33, v168, s[8:9] offset:1792
	global_load_dword v34, v168, s[8:9] offset:2048
	global_load_dword v35, v168, s[8:9] offset:2304
	global_load_dword v36, v168, s[8:9] offset:2560
	global_load_dword v37, v168, s[8:9] offset:2816
	global_load_dword v38, v168, s[8:9] offset:3072
	global_load_dword v39, v168, s[8:9] offset:3328
	global_load_dword v40, v168, s[8:9] offset:3584
	global_load_dword v41, v168, s[8:9] offset:3840
	global_load_dword v42, v168, s[14:15]
	global_load_dword v43, v168, s[14:15] offset:256
	global_load_dword v44, v168, s[14:15] offset:512
	global_load_dword v45, v168, s[14:15] offset:768
	global_load_dword v46, v168, s[14:15] offset:1024
	global_load_dword v47, v168, s[14:15] offset:1280
	global_load_dword v48, v168, s[14:15] offset:1536
	global_load_dword v49, v168, s[14:15] offset:1792
	global_load_dword v50, v168, s[14:15] offset:2048
	global_load_dword v51, v168, s[14:15] offset:2304
	global_load_dword v52, v168, s[14:15] offset:2560
	global_load_dword v53, v168, s[14:15] offset:2816
	global_load_dword v54, v168, s[14:15] offset:3072
	global_load_dword v55, v168, s[14:15] offset:3328
	global_load_dword v56, v168, s[14:15] offset:3584
	global_load_dword v57, v168, s[14:15] offset:3840
	global_load_dword v58, v168, s[46:47]
	global_load_dword v59, v168, s[46:47] offset:256
	global_load_dword v60, v168, s[46:47] offset:512
	global_load_dword v61, v168, s[46:47] offset:768
	global_load_dword v62, v168, s[46:47] offset:1024
	global_load_dword v63, v168, s[46:47] offset:1280
	global_load_dword v64, v168, s[46:47] offset:1536
	global_load_dword v65, v168, s[46:47] offset:1792
	global_load_dword v66, v168, s[46:47] offset:2048
	global_load_dword v67, v168, s[46:47] offset:2304
	global_load_dword v68, v168, s[46:47] offset:2560
	global_load_dword v69, v168, s[46:47] offset:2816
	global_load_dword v70, v168, s[46:47] offset:3072
	global_load_dword v71, v168, s[46:47] offset:3328
	global_load_dword v72, v168, s[46:47] offset:3584
	global_load_dword v73, v168, s[46:47] offset:3840
	global_load_dword v74, v168, s[68:69]
	global_load_dword v75, v168, s[68:69] offset:256
	global_load_dword v76, v168, s[68:69] offset:512
	global_load_dword v77, v168, s[68:69] offset:768
	global_load_dword v78, v168, s[68:69] offset:1024
	global_load_dword v79, v168, s[68:69] offset:1280
	global_load_dword v80, v168, s[68:69] offset:1536
	global_load_dword v81, v168, s[68:69] offset:1792
	global_load_dword v82, v168, s[68:69] offset:2048
	global_load_dword v83, v168, s[68:69] offset:2304
	global_load_dword v84, v168, s[68:69] offset:2560
	global_load_dword v85, v168, s[68:69] offset:2816
	global_load_dword v86, v168, s[68:69] offset:3072
	global_load_dword v87, v168, s[68:69] offset:3328
	global_load_dword v88, v168, s[68:69] offset:3584
	global_load_dword v89, v168, s[68:69] offset:3840
	v_mov_b32_e32 v2, v152
	v_mov_b32_e32 v6, v153
	v_mov_b32_e32 v5, v154
	v_mov_b32_e32 v4, v155
	s_barrier
	s_add_i32 s52, s65, s23
	s_cmpk_gt_i32 s52, 0x7ff
	s_cbranch_scc1 .Lsc_nostage
	s_lshl_b32 s53, s52, 4
	s_and_b32 s53, s53, 0xff0
	s_ashr_i32 s54, s52, 8
	s_and_b32 s55, s52, 0x100
	s_xor_b32 s62, s53, 0xff0
	s_cmp_eq_u32 s55, 0
	s_cselect_b32 s53, s53, s62
	s_add_i32 s55, s53, s10
	s_lshl_b32 s62, s54, 12
	s_add_i32 s55, s55, s62
	v_bfe_u32 v170, v242, 3, 1
	v_or_b32_e32 v170, s55, v170
	v_ashrrev_i32_e32 v171, 31, v170
	v_lshlrev_b64 v[170:171], 10, v[170:171]
	v_lshl_add_u64 v[170:171], v[14:15], 0, v[170:171]
	global_load_dwordx4 v[98:101], v[170:171], off
	global_load_dwordx4 v[94:97], v[170:171], off offset:64
	v_lshrrev_b32_e32 v170, 5, v242
	v_add_u32_e32 v170, s55, v170
	v_ashrrev_i32_e32 v171, 31, v170
	v_lshlrev_b64 v[170:171], 5, v[170:171]
	v_lshl_add_u64 v[170:171], v[16:17], 0, v[170:171]
	global_load_dwordx4 v[90:93], v[170:171], off
	s_lshl_b32 s54, s54, 19
	s_add_u32 s62, s16, s54
	s_addc_u32 s63, s17, 0
	v_lshl_add_u64 v[170:171], s[62:63], 0, v[0:1]
	s_add_i32 m0, s1, 0x0
	s_nop 0
	global_load_lds_dwordx4 v[170:171], off
	v_lshl_add_u64 v[170:171], s[62:63], 0, v[18:19]
	s_add_i32 m0, s1, 0x2000
	s_nop 0
	global_load_lds_dwordx4 v[170:171], off
	v_lshl_add_u64 v[170:171], s[62:63], 0, v[20:21]
	s_add_i32 m0, s1, 0x4000
	s_nop 0
	global_load_lds_dwordx4 v[170:171], off
	v_lshl_add_u64 v[170:171], s[62:63], 0, v[22:23]
	s_add_i32 m0, s1, 0x6000
	s_nop 0
	global_load_lds_dwordx4 v[170:171], off
	s_cmpk_lt_u32 s53, 0xf1
	s_cbranch_scc1 .Lstg_donen
	s_add_u32 s62, s62, 0x8000
	s_addc_u32 s63, s63, 0
	v_lshl_add_u64 v[170:171], s[62:63], 0, v[0:1]
	s_add_i32 m0, s1, 0x8000
	s_nop 0
	global_load_lds_dwordx4 v[170:171], off
	v_lshl_add_u64 v[170:171], s[62:63], 0, v[18:19]
	s_add_i32 m0, s1, 0xa000
	s_nop 0
	global_load_lds_dwordx4 v[170:171], off
	v_lshl_add_u64 v[170:171], s[62:63], 0, v[20:21]
	s_add_i32 m0, s1, 0xc000
	s_nop 0
	global_load_lds_dwordx4 v[170:171], off
	v_lshl_add_u64 v[170:171], s[62:63], 0, v[22:23]
	s_add_i32 m0, s1, 0xe000
	s_nop 0
	global_load_lds_dwordx4 v[170:171], off
.Lstg_donen:
.Lsc_nostage:
	s_mov_b32 s14, 0
	s_mov_b32 s46, 32
	s_mov_b32 s18, 0
	s_branch .LBB0_1055
